# attention epilogue stores (O/l pass and subln-rmsnorm pass) widened to dwordx4: quads formed in dead accumulator/temp registers + permlane32_swap
# speedup vs baseline: 1.0388x; 1.0014x over previous
; __device__ __forceinline__ float bf_lo(unsigned u) { return __uint_as_float(u << 16); }
; __device__ __forceinline__ float bf_hi(unsigned u) { return __uint_as_float(u & 0xffff0000u); }
; __device__ void attn_tile(CP& p, const Grp& G, int s, int hd, int qb, char* lds, float lam) {
;     ...
;     } else {
;       const float i2 = lam / lt;
;       float ssq = 0.f;
; #pragma unroll
;       for (int mb = 0; mb < 4; ++mb)
; #pragma unroll
;         for (int i = 0; i < 4; ++i) {
;           u32x2 w = {0, 0};
;           if (q < L) w = *(const u32x2*)(odst + mb * 32 + 8 * i + 4 * h);
;           const float o0 = bf_lo(w.x) - O[mb][4 * i] * i2, o1v = bf_hi(w.x) - O[mb][4 * i + 1] * i2, o2 = bf_lo(w.y) - O[mb][4 * i + 2] * i2, o3 = bf_hi(w.y) - O[mb][4 * i + 3] * i2;
;           O[mb][4 * i] = o0; O[mb][4 * i + 1] = o1v; O[mb][4 * i + 2] = o2; O[mb][4 * i + 3] = o3;
;           ssq += o0 * o0 + o1v * o1v + o2 * o2 + o3 * o3;
;         }
;       ssq += __shfl_xor(ssq, 32);
.LBB0_441:
	s_or_b64 exec, exec, s[0:1]
	v_div_scale_f32 v64, s[0:1], v128, v128, v163
	v_rcp_f32_e32 v65, v64
	v_div_scale_f32 v68, vcc, v163, v128, v163
	v_fma_f32 v69, -v64, v65, 1.0
	v_fmac_f32_e32 v65, v69, v65
	v_mul_f32_e32 v69, v68, v65
	v_fma_f32 v72, -v64, v69, v68
	v_fmac_f32_e32 v69, v72, v65
	v_fma_f32 v64, -v64, v69, v68
	v_div_fmas_f32 v64, v64, v65, v69
	v_div_fixup_f32 v130, v64, v128, v163
	s_waitcnt vmcnt(0)
	v_lshlrev_b32_e32 v64, 16, v66
	v_and_b32_e32 v65, 0xffff0000, v66
	v_lshlrev_b32_e32 v66, 16, v67
	v_and_b32_e32 v67, 0xffff0000, v67
	v_pk_fma_f32 v[68:69], v[50:51], v[130:131], v[66:67] op_sel_hi:[1,0,1] neg_lo:[1,0,0] neg_hi:[1,0,0]
	v_lshlrev_b32_e32 v66, 16, v70
	v_and_b32_e32 v67, 0xffff0000, v70
	v_lshlrev_b32_e32 v70, 16, v71
	v_and_b32_e32 v71, 0xffff0000, v71
	v_pk_fma_f32 v[64:65], v[48:49], v[130:131], v[64:65] op_sel_hi:[1,0,1] neg_lo:[1,0,0] neg_hi:[1,0,0]
	v_pk_fma_f32 v[66:67], v[52:53], v[130:131], v[66:67] op_sel_hi:[1,0,1] neg_lo:[1,0,0] neg_hi:[1,0,0]
	v_pk_fma_f32 v[72:73], v[54:55], v[130:131], v[70:71] op_sel_hi:[1,0,1] neg_lo:[1,0,0] neg_hi:[1,0,0]
	v_lshlrev_b32_e32 v70, 16, v74
	v_and_b32_e32 v71, 0xffff0000, v74
	v_pk_mul_f32 v[132:133], v[64:65], v[64:65]
	v_pk_mul_f32 v[136:137], v[66:67], v[66:67]
	v_pk_fma_f32 v[70:71], v[56:57], v[130:131], v[70:71] op_sel_hi:[1,0,1] neg_lo:[1,0,0] neg_hi:[1,0,0]
	v_lshlrev_b32_e32 v74, 16, v75
	v_and_b32_e32 v75, 0xffff0000, v75
	v_pk_mul_f32 v[134:135], v[68:69], v[68:69]
	v_pk_mul_f32 v[138:139], v[72:73], v[72:73]
	v_pk_fma_f32 v[78:79], v[58:59], v[130:131], v[74:75] op_sel_hi:[1,0,1] neg_lo:[1,0,0] neg_hi:[1,0,0]
	v_pk_mul_f32 v[140:141], v[70:71], v[70:71]
	v_add_f32_e32 v136, v136, v137
	v_add_f32_e32 v132, v132, v133
	v_pk_mul_f32 v[142:143], v[78:79], v[78:79]
	v_lshlrev_b32_e32 v74, 16, v76
	v_and_b32_e32 v75, 0xffff0000, v76
	v_add_f32_e32 v136, v138, v136
	v_add_f32_e32 v132, v134, v132
	v_add_f32_e32 v133, v140, v141
	v_pk_fma_f32 v[74:75], v[60:61], v[130:131], v[74:75] op_sel_hi:[1,0,1] neg_lo:[1,0,0] neg_hi:[1,0,0]
	v_lshlrev_b32_e32 v76, 16, v77
	v_and_b32_e32 v77, 0xffff0000, v77
	v_add_f32_e32 v136, v139, v136
	v_add_f32_e32 v132, v135, v132
	v_add_f32_e32 v133, v142, v133
	v_pk_fma_f32 v[82:83], v[62:63], v[130:131], v[76:77] op_sel_hi:[1,0,1] neg_lo:[1,0,0] neg_hi:[1,0,0]
	v_pk_mul_f32 v[144:145], v[74:75], v[74:75]
	v_add_f32_e32 v132, v132, v136
	v_add_f32_e32 v133, v143, v133
	v_pk_mul_f32 v[146:147], v[82:83], v[82:83]
	v_lshlrev_b32_e32 v76, 16, v80
	v_and_b32_e32 v77, 0xffff0000, v80
	v_add_f32_e32 v132, v132, v133
	v_add_f32_e32 v133, v144, v145
	v_pk_fma_f32 v[76:77], v[32:33], v[130:131], v[76:77] op_sel_hi:[1,0,1] neg_lo:[1,0,0] neg_hi:[1,0,0]
	v_lshlrev_b32_e32 v80, 16, v81
	v_and_b32_e32 v81, 0xffff0000, v81
	v_add_f32_e32 v133, v146, v133
	v_pk_fma_f32 v[84:85], v[34:35], v[130:131], v[80:81] op_sel_hi:[1,0,1] neg_lo:[1,0,0] neg_hi:[1,0,0]
	v_pk_mul_f32 v[148:149], v[76:77], v[76:77]
	v_add_f32_e32 v133, v147, v133
	v_pk_mul_f32 v[150:151], v[84:85], v[84:85]
	v_lshlrev_b32_e32 v80, 16, v86
	v_and_b32_e32 v81, 0xffff0000, v86
	v_add_f32_e32 v132, v132, v133
	v_add_f32_e32 v133, v148, v149
	v_pk_fma_f32 v[80:81], v[36:37], v[130:131], v[80:81] op_sel_hi:[1,0,1] neg_lo:[1,0,0] neg_hi:[1,0,0]
	v_lshlrev_b32_e32 v86, 16, v87
	v_and_b32_e32 v87, 0xffff0000, v87
	v_add_f32_e32 v133, v150, v133
	v_pk_fma_f32 v[88:89], v[38:39], v[130:131], v[86:87] op_sel_hi:[1,0,1] neg_lo:[1,0,0] neg_hi:[1,0,0]
	v_pk_mul_f32 v[152:153], v[80:81], v[80:81]
	v_add_f32_e32 v133, v151, v133
	v_pk_mul_f32 v[154:155], v[88:89], v[88:89]
	v_lshlrev_b32_e32 v86, 16, v90
	v_and_b32_e32 v87, 0xffff0000, v90
	v_add_f32_e32 v132, v132, v133
	v_add_f32_e32 v133, v152, v153
	v_pk_fma_f32 v[86:87], v[40:41], v[130:131], v[86:87] op_sel_hi:[1,0,1] neg_lo:[1,0,0] neg_hi:[1,0,0]
	v_lshlrev_b32_e32 v90, 16, v91
	v_and_b32_e32 v91, 0xffff0000, v91
	v_add_f32_e32 v133, v154, v133
	v_pk_fma_f32 v[94:95], v[42:43], v[130:131], v[90:91] op_sel_hi:[1,0,1] neg_lo:[1,0,0] neg_hi:[1,0,0]
	v_pk_mul_f32 v[156:157], v[86:87], v[86:87]
	v_add_f32_e32 v133, v155, v133
	v_pk_mul_f32 v[158:159], v[94:95], v[94:95]
	v_lshlrev_b32_e32 v90, 16, v92
	v_and_b32_e32 v91, 0xffff0000, v92
	v_add_f32_e32 v132, v132, v133
	v_add_f32_e32 v133, v156, v157
	v_pk_fma_f32 v[90:91], v[44:45], v[130:131], v[90:91] op_sel_hi:[1,0,1] neg_lo:[1,0,0] neg_hi:[1,0,0]
	v_lshlrev_b32_e32 v92, 16, v93
	v_and_b32_e32 v93, 0xffff0000, v93
	v_add_f32_e32 v133, v158, v133
	v_pk_fma_f32 v[98:99], v[46:47], v[130:131], v[92:93] op_sel_hi:[1,0,1] neg_lo:[1,0,0] neg_hi:[1,0,0]
	v_pk_mul_f32 v[190:191], v[90:91], v[90:91]
	v_add_f32_e32 v133, v159, v133
	v_pk_mul_f32 v[192:193], v[98:99], v[98:99]
	v_lshlrev_b32_e32 v92, 16, v96
	v_and_b32_e32 v93, 0xffff0000, v96
	v_add_f32_e32 v132, v132, v133
	v_add_f32_e32 v133, v190, v191
	v_pk_fma_f32 v[92:93], v[16:17], v[130:131], v[92:93] op_sel_hi:[1,0,1] neg_lo:[1,0,0] neg_hi:[1,0,0]
	v_lshlrev_b32_e32 v96, 16, v97
	v_and_b32_e32 v97, 0xffff0000, v97
	v_add_f32_e32 v133, v192, v133
	v_pk_fma_f32 v[100:101], v[18:19], v[130:131], v[96:97] op_sel_hi:[1,0,1] neg_lo:[1,0,0] neg_hi:[1,0,0]
	v_pk_mul_f32 v[194:195], v[92:93], v[92:93]
	v_add_f32_e32 v133, v193, v133
	v_pk_mul_f32 v[196:197], v[100:101], v[100:101]
	v_lshlrev_b32_e32 v96, 16, v102
	v_and_b32_e32 v97, 0xffff0000, v102
	v_add_f32_e32 v132, v132, v133
	v_add_f32_e32 v133, v194, v195
	v_pk_fma_f32 v[96:97], v[20:21], v[130:131], v[96:97] op_sel_hi:[1,0,1] neg_lo:[1,0,0] neg_hi:[1,0,0]
	v_lshlrev_b32_e32 v102, 16, v103
	v_and_b32_e32 v103, 0xffff0000, v103
	v_add_f32_e32 v133, v196, v133
; __device__ __forceinline__ float bf_lo(unsigned u) { return __uint_as_float(u << 16); }
; __device__ __forceinline__ float bf_hi(unsigned u) { return __uint_as_float(u & 0xffff0000u); }
; __device__ void attn_tile(CP& p, const Grp& G, int s, int hd, int qb, char* lds, float lam) {
;     ...
;           const float o0 = bf_lo(w.x) - O[mb][4 * i] * i2, o1v = bf_hi(w.x) - O[mb][4 * i + 1] * i2, o2 = bf_lo(w.y) - O[mb][4 * i + 2] * i2, o3 = bf_hi(w.y) - O[mb][4 * i + 3] * i2;
;           O[mb][4 * i] = o0; O[mb][4 * i + 1] = o1v; O[mb][4 * i + 2] = o2; O[mb][4 * i + 3] = o3;
;           ssq += o0 * o0 + o1v * o1v + o2 * o2 + o3 * o3;
;         }
;       ssq += __shfl_xor(ssq, 32);
;       const float rn = rsqrtf(ssq * (1.f / 128.f) + EPSN) * 0.8f;
;       if (q < L) {
; #pragma unroll
;         for (int mb = 0; mb < 4; ++mb)
; #pragma unroll
;           for (int i = 0; i < 4; ++i) {
;             const int dv = mb * 32 + 8 * i + 4 * h;
;             const f32x4 g = *(const f32x4*)(p.subln + dv);
;             *(u32x2*)(odst + dv) = (u32x2){pk_bf16(O[mb][4 * i] * rn * g.x, O[mb][4 * i + 1] * rn * g.y),
;                                            pk_bf16(O[mb][4 * i + 2] * rn * g.z, O[mb][4 * i + 3] * rn * g.w)};
;           }
	v_pk_fma_f32 v[104:105], v[22:23], v[130:131], v[102:103] op_sel_hi:[1,0,1] neg_lo:[1,0,0] neg_hi:[1,0,0]
	v_pk_mul_f32 v[198:199], v[96:97], v[96:97]
	v_add_f32_e32 v133, v197, v133
	v_pk_mul_f32 v[200:201], v[104:105], v[104:105]
	v_lshlrev_b32_e32 v102, 16, v106
	v_and_b32_e32 v103, 0xffff0000, v106
	v_add_f32_e32 v132, v132, v133
	v_add_f32_e32 v133, v198, v199
	v_pk_fma_f32 v[102:103], v[24:25], v[130:131], v[102:103] op_sel_hi:[1,0,1] neg_lo:[1,0,0] neg_hi:[1,0,0]
	v_lshlrev_b32_e32 v106, 16, v107
	v_and_b32_e32 v107, 0xffff0000, v107
	v_add_f32_e32 v133, v200, v133
	v_pk_fma_f32 v[110:111], v[26:27], v[130:131], v[106:107] op_sel_hi:[1,0,1] neg_lo:[1,0,0] neg_hi:[1,0,0]
	v_pk_mul_f32 v[202:203], v[102:103], v[102:103]
	v_add_f32_e32 v133, v201, v133
	v_pk_mul_f32 v[232:233], v[110:111], v[110:111]
	v_lshlrev_b32_e32 v106, 16, v108
	v_and_b32_e32 v107, 0xffff0000, v108
	v_add_f32_e32 v132, v132, v133
	v_add_f32_e32 v133, v202, v203
	v_pk_fma_f32 v[106:107], v[28:29], v[130:131], v[106:107] op_sel_hi:[1,0,1] neg_lo:[1,0,0] neg_hi:[1,0,0]
	v_lshlrev_b32_e32 v108, 16, v109
	v_and_b32_e32 v109, 0xffff0000, v109
	v_add_f32_e32 v133, v232, v133
	v_pk_fma_f32 v[114:115], v[30:31], v[130:131], v[108:109] op_sel_hi:[1,0,1] neg_lo:[1,0,0] neg_hi:[1,0,0]
	v_pk_mul_f32 v[234:235], v[106:107], v[106:107]
	v_add_f32_e32 v133, v233, v133
	v_pk_mul_f32 v[236:237], v[114:115], v[114:115]
	v_lshlrev_b32_e32 v108, 16, v112
	v_and_b32_e32 v109, 0xffff0000, v112
	v_add_f32_e32 v132, v132, v133
	v_add_f32_e32 v133, v234, v235
	v_pk_fma_f32 v[108:109], v[0:1], v[130:131], v[108:109] op_sel_hi:[1,0,1] neg_lo:[1,0,0] neg_hi:[1,0,0]
	v_lshlrev_b32_e32 v112, 16, v113
	v_and_b32_e32 v113, 0xffff0000, v113
	v_add_f32_e32 v133, v236, v133
	v_pk_fma_f32 v[116:117], v[2:3], v[130:131], v[112:113] op_sel_hi:[1,0,1] neg_lo:[1,0,0] neg_hi:[1,0,0]
	v_pk_mul_f32 v[238:239], v[108:109], v[108:109]
	v_add_f32_e32 v133, v237, v133
	v_pk_mul_f32 v[240:241], v[116:117], v[116:117]
	v_lshlrev_b32_e32 v112, 16, v118
	v_and_b32_e32 v113, 0xffff0000, v118
	v_add_f32_e32 v132, v132, v133
	v_add_f32_e32 v133, v238, v239
	v_pk_fma_f32 v[112:113], v[4:5], v[130:131], v[112:113] op_sel_hi:[1,0,1] neg_lo:[1,0,0] neg_hi:[1,0,0]
	v_lshlrev_b32_e32 v118, 16, v119
	v_and_b32_e32 v119, 0xffff0000, v119
	v_add_f32_e32 v133, v240, v133
	v_pk_fma_f32 v[120:121], v[6:7], v[130:131], v[118:119] op_sel_hi:[1,0,1] neg_lo:[1,0,0] neg_hi:[1,0,0]
	v_pk_mul_f32 v[242:243], v[112:113], v[112:113]
	v_add_f32_e32 v133, v241, v133
	v_pk_mul_f32 v[244:245], v[120:121], v[120:121]
	v_lshlrev_b32_e32 v118, 16, v122
	v_and_b32_e32 v119, 0xffff0000, v122
	v_lshlrev_b32_e32 v122, 16, v123
	v_and_b32_e32 v123, 0xffff0000, v123
	v_add_f32_e32 v132, v132, v133
	v_add_f32_e32 v133, v242, v243
	v_pk_fma_f32 v[118:119], v[8:9], v[130:131], v[118:119] op_sel_hi:[1,0,1] neg_lo:[1,0,0] neg_hi:[1,0,0]
	v_pk_fma_f32 v[124:125], v[10:11], v[130:131], v[122:123] op_sel_hi:[1,0,1] neg_lo:[1,0,0] neg_hi:[1,0,0]
	v_lshlrev_b32_e32 v122, 16, v126
	v_and_b32_e32 v123, 0xffff0000, v126
	v_add_f32_e32 v133, v244, v133
	v_pk_mul_f32 v[246:247], v[118:119], v[118:119]
	v_pk_fma_f32 v[122:123], v[12:13], v[130:131], v[122:123] op_sel_hi:[1,0,1] neg_lo:[1,0,0] neg_hi:[1,0,0]
	v_lshlrev_b32_e32 v126, 16, v127
	v_and_b32_e32 v127, 0xffff0000, v127
	v_add_f32_e32 v133, v245, v133
	v_pk_mul_f32 v[248:249], v[124:125], v[124:125]
	v_pk_fma_f32 v[126:127], v[14:15], v[130:131], v[126:127] op_sel_hi:[1,0,1] neg_lo:[1,0,0] neg_hi:[1,0,0]
	v_pk_mul_f32 v[130:131], v[122:123], v[122:123]
	v_add_f32_e32 v132, v132, v133
	v_add_f32_e32 v133, v246, v247
	v_pk_mul_f32 v[250:251], v[126:127], v[126:127]
	v_add_f32_e32 v133, v248, v133
	v_add_f32_e32 v130, v130, v131
	v_add_f32_e32 v133, v249, v133
	v_add_f32_e32 v130, v250, v130
	v_add_f32_e32 v132, v132, v133
	v_add_f32_e32 v130, v251, v130
	v_add_f32_e32 v130, v132, v130
	ds_bpermute_b32 v129, v129, v130
	s_and_saveexec_b64 s[34:35], s[38:39]
	s_cbranch_execz .LBB0_443
	global_load_dwordx4 v[132:135], v[176:177], off
	s_waitcnt lgkmcnt(0)
	v_add_f32_e32 v129, v130, v129
	v_fmamk_f32 v129, v129, 0x3c000000, v205
	v_mul_f32_e32 v130, 0x4b800000, v129
	v_cmp_gt_f32_e32 vcc, s21, v129
	s_nop 1
	v_cndmask_b32_e32 v129, v129, v130, vcc
	v_rsq_f32_e32 v129, v129
	s_nop 0
	v_mul_f32_e32 v130, 0x45800000, v129
	v_cndmask_b32_e32 v129, v129, v130, vcc
	v_mul_f32_e32 v136, 0x3f4ccccd, v129
	v_pk_mul_f32 v[64:65], v[64:65], v[136:137] op_sel_hi:[1,0]
	v_pk_mul_f32 v[68:69], v[68:69], v[136:137] op_sel_hi:[1,0]
	s_waitcnt vmcnt(0)
	v_pk_mul_f32 v[64:65], v[64:65], v[132:133]
	v_pk_mul_f32 v[68:69], v[68:69], v[134:135]
	v_cvt_pk_bf16_f32 v64, v64, v65
	v_cvt_pk_bf16_f32 v65, v68, v69
	v_mbcnt_lo_u32_b32 v250, -1, 0
	v_mbcnt_hi_u32_b32 v250, -1, v250
	v_lshrrev_b32_e32 v250, 2, v250
	v_and_b32_e32 v250, 8, v250
	v_mov_b32_e32 v251, 0
	v_lshl_add_u64 v[250:251], v[174:175], 0, v[250:251]
	v_mov_b32_e32 v238, v64
	v_mov_b32_e32 v239, v65
	global_load_dwordx4 v[130:133], v[176:177], off offset:32
	v_pk_mul_f32 v[64:65], v[66:67], v[136:137] op_sel_hi:[1,0]
	v_pk_mul_f32 v[66:67], v[72:73], v[136:137] op_sel_hi:[1,0]
	v_pk_mul_f32 v[68:69], v[70:71], v[136:137] op_sel_hi:[1,0]
	v_pk_mul_f32 v[70:71], v[78:79], v[136:137] op_sel_hi:[1,0]
	s_waitcnt vmcnt(0)
	v_pk_mul_f32 v[64:65], v[64:65], v[130:131]
	v_pk_mul_f32 v[66:67], v[66:67], v[132:133]
	v_cvt_pk_bf16_f32 v64, v64, v65
	v_cvt_pk_bf16_f32 v65, v66, v67
	v_mov_b32_e32 v240, v64
	v_mov_b32_e32 v241, v65
	s_nop 1
	v_permlane32_swap_b32_e32 v238, v240
	v_permlane32_swap_b32_e32 v239, v241
	global_store_dwordx4 v[250:251], v[238:241], off
	global_load_dwordx4 v[64:67], v[176:177], off offset:64
	s_waitcnt vmcnt(0)
; __device__ void attn_tile(CP& p, const Grp& G, int s, int hd, int qb, char* lds, float lam) {
;     ...
;       if (q < L) {
; #pragma unroll
;         for (int mb = 0; mb < 4; ++mb)
; #pragma unroll
;           for (int i = 0; i < 4; ++i) {
;             const int dv = mb * 32 + 8 * i + 4 * h;
;             const f32x4 g = *(const f32x4*)(p.subln + dv);
;             *(u32x2*)(odst + dv) = (u32x2){pk_bf16(O[mb][4 * i] * rn * g.x, O[mb][4 * i + 1] * rn * g.y),
;                                            pk_bf16(O[mb][4 * i + 2] * rn * g.z, O[mb][4 * i + 3] * rn * g.w)};
;           }
	v_pk_mul_f32 v[64:65], v[68:69], v[64:65]
	v_pk_mul_f32 v[66:67], v[70:71], v[66:67]
	v_cvt_pk_bf16_f32 v64, v64, v65
	v_cvt_pk_bf16_f32 v65, v66, v67
	v_mov_b32_e32 v242, v64
	v_mov_b32_e32 v243, v65
	global_load_dwordx4 v[64:67], v[176:177], off offset:96
	v_pk_mul_f32 v[68:69], v[74:75], v[136:137] op_sel_hi:[1,0]
	v_pk_mul_f32 v[70:71], v[82:83], v[136:137] op_sel_hi:[1,0]
	s_waitcnt vmcnt(0)
	v_pk_mul_f32 v[64:65], v[68:69], v[64:65]
	v_pk_mul_f32 v[66:67], v[70:71], v[66:67]
	v_cvt_pk_bf16_f32 v64, v64, v65
	v_cvt_pk_bf16_f32 v65, v66, v67
	v_mov_b32_e32 v244, v64
	v_mov_b32_e32 v245, v65
	s_nop 1
	v_permlane32_swap_b32_e32 v242, v244
	v_permlane32_swap_b32_e32 v243, v245
	global_store_dwordx4 v[250:251], v[242:245], off offset:32
	global_load_dwordx4 v[64:67], v[176:177], off offset:128
	v_pk_mul_f32 v[68:69], v[76:77], v[136:137] op_sel_hi:[1,0]
	v_pk_mul_f32 v[70:71], v[84:85], v[136:137] op_sel_hi:[1,0]
	s_waitcnt vmcnt(0)
	v_pk_mul_f32 v[64:65], v[68:69], v[64:65]
	v_pk_mul_f32 v[66:67], v[70:71], v[66:67]
	v_cvt_pk_bf16_f32 v64, v64, v65
	v_cvt_pk_bf16_f32 v65, v66, v67
	v_mov_b32_e32 v246, v64
	v_mov_b32_e32 v247, v65
	global_load_dwordx4 v[64:67], v[176:177], off offset:160
	v_pk_mul_f32 v[68:69], v[80:81], v[136:137] op_sel_hi:[1,0]
	v_pk_mul_f32 v[70:71], v[88:89], v[136:137] op_sel_hi:[1,0]
	s_waitcnt vmcnt(0)
	v_pk_mul_f32 v[64:65], v[68:69], v[64:65]
	v_pk_mul_f32 v[66:67], v[70:71], v[66:67]
	v_cvt_pk_bf16_f32 v64, v64, v65
	v_cvt_pk_bf16_f32 v65, v66, v67
	v_mov_b32_e32 v248, v64
	v_mov_b32_e32 v249, v65
	s_nop 1
	v_permlane32_swap_b32_e32 v246, v248
	v_permlane32_swap_b32_e32 v247, v249
	global_store_dwordx4 v[250:251], v[246:249], off offset:64
	global_load_dwordx4 v[64:67], v[176:177], off offset:192
	v_pk_mul_f32 v[68:69], v[86:87], v[136:137] op_sel_hi:[1,0]
	v_pk_mul_f32 v[70:71], v[94:95], v[136:137] op_sel_hi:[1,0]
	s_waitcnt vmcnt(0)
	v_pk_mul_f32 v[64:65], v[68:69], v[64:65]
	v_pk_mul_f32 v[66:67], v[70:71], v[66:67]
	v_cvt_pk_bf16_f32 v64, v64, v65
	v_cvt_pk_bf16_f32 v65, v66, v67
	v_mov_b32_e32 v238, v64
	v_mov_b32_e32 v239, v65
	global_load_dwordx4 v[64:67], v[176:177], off offset:224
	v_pk_mul_f32 v[68:69], v[90:91], v[136:137] op_sel_hi:[1,0]
	v_pk_mul_f32 v[70:71], v[98:99], v[136:137] op_sel_hi:[1,0]
	s_waitcnt vmcnt(0)
	v_pk_mul_f32 v[64:65], v[68:69], v[64:65]
	v_pk_mul_f32 v[66:67], v[70:71], v[66:67]
	v_cvt_pk_bf16_f32 v64, v64, v65
	v_cvt_pk_bf16_f32 v65, v66, v67
	v_mov_b32_e32 v240, v64
	v_mov_b32_e32 v241, v65
	s_nop 1
	v_permlane32_swap_b32_e32 v238, v240
	v_permlane32_swap_b32_e32 v239, v241
	global_store_dwordx4 v[250:251], v[238:241], off offset:96
	global_load_dwordx4 v[64:67], v[176:177], off offset:256
	v_pk_mul_f32 v[68:69], v[92:93], v[136:137] op_sel_hi:[1,0]
	v_pk_mul_f32 v[70:71], v[100:101], v[136:137] op_sel_hi:[1,0]
	s_waitcnt vmcnt(0)
	v_pk_mul_f32 v[64:65], v[68:69], v[64:65]
	v_pk_mul_f32 v[66:67], v[70:71], v[66:67]
	v_cvt_pk_bf16_f32 v64, v64, v65
	v_cvt_pk_bf16_f32 v65, v66, v67
	v_mov_b32_e32 v242, v64
	v_mov_b32_e32 v243, v65
	global_load_dwordx4 v[64:67], v[176:177], off offset:288
	v_pk_mul_f32 v[68:69], v[96:97], v[136:137] op_sel_hi:[1,0]
	v_pk_mul_f32 v[70:71], v[104:105], v[136:137] op_sel_hi:[1,0]
	s_waitcnt vmcnt(0)
	v_pk_mul_f32 v[64:65], v[68:69], v[64:65]
	v_pk_mul_f32 v[66:67], v[70:71], v[66:67]
	v_cvt_pk_bf16_f32 v64, v64, v65
	v_cvt_pk_bf16_f32 v65, v66, v67
	v_mov_b32_e32 v244, v64
	v_mov_b32_e32 v245, v65
	s_nop 1
	v_permlane32_swap_b32_e32 v242, v244
	v_permlane32_swap_b32_e32 v243, v245
	global_store_dwordx4 v[250:251], v[242:245], off offset:128
	global_load_dwordx4 v[64:67], v[176:177], off offset:320
	v_pk_mul_f32 v[68:69], v[102:103], v[136:137] op_sel_hi:[1,0]
	v_pk_mul_f32 v[70:71], v[110:111], v[136:137] op_sel_hi:[1,0]
	s_waitcnt vmcnt(0)
	v_pk_mul_f32 v[64:65], v[68:69], v[64:65]
	v_pk_mul_f32 v[66:67], v[70:71], v[66:67]
	v_cvt_pk_bf16_f32 v64, v64, v65
	v_cvt_pk_bf16_f32 v65, v66, v67
	v_mov_b32_e32 v246, v64
	v_mov_b32_e32 v247, v65
	global_load_dwordx4 v[64:67], v[176:177], off offset:352
	v_pk_mul_f32 v[68:69], v[106:107], v[136:137] op_sel_hi:[1,0]
	v_pk_mul_f32 v[70:71], v[114:115], v[136:137] op_sel_hi:[1,0]
	s_waitcnt vmcnt(0)
	v_pk_mul_f32 v[64:65], v[68:69], v[64:65]
	v_pk_mul_f32 v[66:67], v[70:71], v[66:67]
	v_cvt_pk_bf16_f32 v64, v64, v65
	v_cvt_pk_bf16_f32 v65, v66, v67
	v_mov_b32_e32 v248, v64
	v_mov_b32_e32 v249, v65
	s_nop 1
	v_permlane32_swap_b32_e32 v246, v248
	v_permlane32_swap_b32_e32 v247, v249
	global_store_dwordx4 v[250:251], v[246:249], off offset:160
	global_load_dwordx4 v[64:67], v[176:177], off offset:384
	v_pk_mul_f32 v[68:69], v[108:109], v[136:137] op_sel_hi:[1,0]
	v_pk_mul_f32 v[70:71], v[116:117], v[136:137] op_sel_hi:[1,0]
	s_waitcnt vmcnt(0)
	v_pk_mul_f32 v[64:65], v[68:69], v[64:65]
	v_pk_mul_f32 v[66:67], v[70:71], v[66:67]
	v_cvt_pk_bf16_f32 v64, v64, v65
	v_cvt_pk_bf16_f32 v65, v66, v67
	v_mov_b32_e32 v238, v64
	v_mov_b32_e32 v239, v65
	global_load_dwordx4 v[64:67], v[176:177], off offset:416
	v_pk_mul_f32 v[68:69], v[112:113], v[136:137] op_sel_hi:[1,0]
	v_pk_mul_f32 v[70:71], v[120:121], v[136:137] op_sel_hi:[1,0]
	s_waitcnt vmcnt(0)
	v_pk_mul_f32 v[64:65], v[68:69], v[64:65]
	v_pk_mul_f32 v[66:67], v[70:71], v[66:67]
	v_cvt_pk_bf16_f32 v64, v64, v65
	v_cvt_pk_bf16_f32 v65, v66, v67
	v_mov_b32_e32 v240, v64
	v_mov_b32_e32 v241, v65
	s_nop 1
	v_permlane32_swap_b32_e32 v238, v240
	v_permlane32_swap_b32_e32 v239, v241
	global_store_dwordx4 v[250:251], v[238:241], off offset:192
	global_load_dwordx4 v[64:67], v[176:177], off offset:448
	v_pk_mul_f32 v[68:69], v[118:119], v[136:137] op_sel_hi:[1,0]
	v_pk_mul_f32 v[70:71], v[124:125], v[136:137] op_sel_hi:[1,0]
	s_waitcnt vmcnt(0)
	v_pk_mul_f32 v[64:65], v[68:69], v[64:65]
	v_pk_mul_f32 v[66:67], v[70:71], v[66:67]
	v_cvt_pk_bf16_f32 v64, v64, v65
	v_cvt_pk_bf16_f32 v65, v66, v67
	v_mov_b32_e32 v242, v64
	v_mov_b32_e32 v243, v65
	global_load_dwordx4 v[64:67], v[176:177], off offset:480
	v_pk_mul_f32 v[68:69], v[122:123], v[136:137] op_sel_hi:[1,0]
	v_pk_mul_f32 v[70:71], v[126:127], v[136:137] op_sel_hi:[1,0]
	s_waitcnt vmcnt(0)
	v_pk_mul_f32 v[64:65], v[68:69], v[64:65]
	v_pk_mul_f32 v[66:67], v[70:71], v[66:67]
	v_cvt_pk_bf16_f32 v64, v64, v65
	v_cvt_pk_bf16_f32 v65, v66, v67
	v_mov_b32_e32 v244, v64
	v_mov_b32_e32 v245, v65
	s_nop 1
	v_permlane32_swap_b32_e32 v242, v244
	v_permlane32_swap_b32_e32 v243, v245
	global_store_dwordx4 v[250:251], v[242:245], off offset:224

; __device__ void attn_tile(CP& p, const Grp& G, int s, int hd, int qb, char* lds, float lam) {
;     ...
;     const float lt = lrun + __shfl_xor(lrun, 32);
;     if (br == 0) {
;       const float i1 = 1.f / lt;
; #pragma unroll
;       for (int mb = 0; mb < 4; ++mb)
; #pragma unroll
;         for (int i = 0; i < 4; ++i)
;           if (q < L) *(u32x2*)(odst + mb * 32 + 8 * i + 4 * h) = (u32x2){pk_bf16(O[mb][4 * i] * i1, O[mb][4 * i + 1] * i1), pk_bf16(O[mb][4 * i + 2] * i1, O[mb][4 * i + 3] * i1)};
.LBB0_444:
	s_and_b64 vcc, exec, s[0:1]
	s_cbranch_vccz .LBB0_368
	s_and_saveexec_b64 s[6:7], s[38:39]
	s_cbranch_execz .LBB0_367
	v_div_scale_f32 v64, s[0:1], v128, v128, 1.0
	v_rcp_f32_e32 v65, v64
	v_div_scale_f32 v66, vcc, 1.0, v128, 1.0
	v_fma_f32 v67, -v64, v65, 1.0
	v_fmac_f32_e32 v65, v67, v65
	v_mul_f32_e32 v67, v66, v65
	v_fma_f32 v68, -v64, v67, v66
	v_fmac_f32_e32 v67, v68, v65
	v_fma_f32 v64, -v64, v67, v66
	v_div_fmas_f32 v64, v64, v65, v67
	v_div_fixup_f32 v64, v64, v128, 1.0
	v_mov_b32_e32 v68, v64
	v_mbcnt_lo_u32_b32 v66, -1, 0
	v_mbcnt_hi_u32_b32 v66, -1, v66
	v_lshrrev_b32_e32 v66, 2, v66
	v_and_b32_e32 v66, 8, v66
	v_mov_b32_e32 v67, 0
	v_lshl_add_u64 v[66:67], v[174:175], 0, v[66:67]
	v_pk_mul_f32 v[48:49], v[48:49], v[68:69] op_sel_hi:[1,0]
	v_pk_mul_f32 v[50:51], v[50:51], v[68:69] op_sel_hi:[1,0]
	v_cvt_pk_bf16_f32 v48, v48, v49
	v_cvt_pk_bf16_f32 v49, v50, v51
	v_pk_mul_f32 v[50:51], v[52:53], v[68:69] op_sel_hi:[1,0]
	v_pk_mul_f32 v[64:65], v[54:55], v[68:69] op_sel_hi:[1,0]
	v_cvt_pk_bf16_f32 v50, v50, v51
	v_cvt_pk_bf16_f32 v51, v64, v65
	s_nop 1
	v_permlane32_swap_b32_e32 v48, v50
	v_permlane32_swap_b32_e32 v49, v51
	global_store_dwordx4 v[66:67], v[48:51], off
	v_pk_mul_f32 v[32:33], v[32:33], v[68:69] op_sel_hi:[1,0]
	v_pk_mul_f32 v[34:35], v[34:35], v[68:69] op_sel_hi:[1,0]
	v_cvt_pk_bf16_f32 v32, v32, v33
	v_cvt_pk_bf16_f32 v33, v34, v35
	v_pk_mul_f32 v[34:35], v[36:37], v[68:69] op_sel_hi:[1,0]
	v_pk_mul_f32 v[64:65], v[38:39], v[68:69] op_sel_hi:[1,0]
	v_cvt_pk_bf16_f32 v34, v34, v35
	v_cvt_pk_bf16_f32 v35, v64, v65
	s_nop 1
	v_permlane32_swap_b32_e32 v32, v34
	v_permlane32_swap_b32_e32 v33, v35
	global_store_dwordx4 v[66:67], v[32:35], off offset:64
	v_pk_mul_f32 v[16:17], v[16:17], v[68:69] op_sel_hi:[1,0]
	v_pk_mul_f32 v[18:19], v[18:19], v[68:69] op_sel_hi:[1,0]
	v_cvt_pk_bf16_f32 v16, v16, v17
	v_cvt_pk_bf16_f32 v17, v18, v19
	v_pk_mul_f32 v[18:19], v[20:21], v[68:69] op_sel_hi:[1,0]
	v_pk_mul_f32 v[64:65], v[22:23], v[68:69] op_sel_hi:[1,0]
	v_cvt_pk_bf16_f32 v18, v18, v19
	v_cvt_pk_bf16_f32 v19, v64, v65
	s_nop 1
	v_permlane32_swap_b32_e32 v16, v18
	v_permlane32_swap_b32_e32 v17, v19
	global_store_dwordx4 v[66:67], v[16:19], off offset:128
	v_pk_mul_f32 v[0:1], v[0:1], v[68:69] op_sel_hi:[1,0]
	v_pk_mul_f32 v[2:3], v[2:3], v[68:69] op_sel_hi:[1,0]
	v_cvt_pk_bf16_f32 v0, v0, v1
	v_cvt_pk_bf16_f32 v1, v2, v3
	v_pk_mul_f32 v[2:3], v[4:5], v[68:69] op_sel_hi:[1,0]
	v_pk_mul_f32 v[64:65], v[6:7], v[68:69] op_sel_hi:[1,0]
	v_cvt_pk_bf16_f32 v2, v2, v3
	v_cvt_pk_bf16_f32 v3, v64, v65
	s_nop 1
	v_permlane32_swap_b32_e32 v0, v2
	v_permlane32_swap_b32_e32 v1, v3
	global_store_dwordx4 v[66:67], v[0:3], off offset:192
	v_pk_mul_f32 v[48:49], v[56:57], v[68:69] op_sel_hi:[1,0]
	v_pk_mul_f32 v[50:51], v[58:59], v[68:69] op_sel_hi:[1,0]
	v_cvt_pk_bf16_f32 v48, v48, v49
	v_cvt_pk_bf16_f32 v49, v50, v51
	v_pk_mul_f32 v[50:51], v[60:61], v[68:69] op_sel_hi:[1,0]
	v_pk_mul_f32 v[64:65], v[62:63], v[68:69] op_sel_hi:[1,0]
	v_cvt_pk_bf16_f32 v50, v50, v51
	v_cvt_pk_bf16_f32 v51, v64, v65
	s_nop 1
	v_permlane32_swap_b32_e32 v48, v50
	v_permlane32_swap_b32_e32 v49, v51
	global_store_dwordx4 v[66:67], v[48:51], off offset:32
	v_pk_mul_f32 v[32:33], v[40:41], v[68:69] op_sel_hi:[1,0]
	v_pk_mul_f32 v[34:35], v[42:43], v[68:69] op_sel_hi:[1,0]
	v_cvt_pk_bf16_f32 v32, v32, v33
	v_cvt_pk_bf16_f32 v33, v34, v35
	v_pk_mul_f32 v[34:35], v[44:45], v[68:69] op_sel_hi:[1,0]
	v_pk_mul_f32 v[64:65], v[46:47], v[68:69] op_sel_hi:[1,0]
	v_cvt_pk_bf16_f32 v34, v34, v35
	v_cvt_pk_bf16_f32 v35, v64, v65
	s_nop 1
	v_permlane32_swap_b32_e32 v32, v34
	v_permlane32_swap_b32_e32 v33, v35
	global_store_dwordx4 v[66:67], v[32:35], off offset:96
	v_pk_mul_f32 v[16:17], v[24:25], v[68:69] op_sel_hi:[1,0]
	v_pk_mul_f32 v[18:19], v[26:27], v[68:69] op_sel_hi:[1,0]
	v_cvt_pk_bf16_f32 v16, v16, v17
	v_cvt_pk_bf16_f32 v17, v18, v19
	v_pk_mul_f32 v[18:19], v[28:29], v[68:69] op_sel_hi:[1,0]
	v_pk_mul_f32 v[64:65], v[30:31], v[68:69] op_sel_hi:[1,0]
	v_cvt_pk_bf16_f32 v18, v18, v19
	v_cvt_pk_bf16_f32 v19, v64, v65
	s_nop 1
	v_permlane32_swap_b32_e32 v16, v18
	v_permlane32_swap_b32_e32 v17, v19
	global_store_dwordx4 v[66:67], v[16:19], off offset:160
	v_pk_mul_f32 v[0:1], v[8:9], v[68:69] op_sel_hi:[1,0]
	v_pk_mul_f32 v[2:3], v[10:11], v[68:69] op_sel_hi:[1,0]
	v_cvt_pk_bf16_f32 v0, v0, v1
	v_cvt_pk_bf16_f32 v1, v2, v3
	v_pk_mul_f32 v[2:3], v[12:13], v[68:69] op_sel_hi:[1,0]
	v_pk_mul_f32 v[64:65], v[14:15], v[68:69] op_sel_hi:[1,0]
	v_cvt_pk_bf16_f32 v2, v2, v3
	v_cvt_pk_bf16_f32 v3, v64, v65
	s_nop 1
	v_permlane32_swap_b32_e32 v0, v2
	v_permlane32_swap_b32_e32 v1, v3
	global_store_dwordx4 v[66:67], v[0:3], off offset:224
	s_branch .LBB0_367
